# XCD-local barrier (no L2 writeback / top-level counter) for the 6 GEMM->GEMM transitions whose tiles stay in one XCD
# speedup vs baseline: 1.0013x; 1.0013x over previous
.LBB0_1531:
	s_andn2_saveexec_b64 s[4:5], s[8:9]
	s_cbranch_execz .LBB0_1551
	s_mov_b64 s[8:9], exec
	s_lshr_b32 s4, 0x31820100, s74
	s_and_b32 s4, s4, 1
	s_cmp_lg_u32 s4, 0
	s_cbranch_scc1 .LBB0_1548
	buffer_wbl2 sc1
	s_waitcnt lgkmcnt(0)
	s_waitcnt vmcnt(0)
	v_mbcnt_lo_u32_b32 v0, s8, 0
	v_mbcnt_hi_u32_b32 v0, s9, v0
	v_cmp_eq_u32_e32 vcc, 0, v0
	s_and_saveexec_b64 s[10:11], vcc
	s_cbranch_execz .LBB0_1534
	s_bcnt1_i32_b64 s4, s[8:9]
	v_mov_b32_e32 v3, s4
	v_readlane_b32 s4, v253, 12
	v_readlane_b32 s5, v253, 13
	s_nop 4
	global_atomic_add v3, v1, v3, s[4:5] sc0
